# robustness: s_nop between a VMEM store and a directly following s_waitcnt vmcnt in the hand-written last-layer resid pass (3 sites); otherwise identical to v072
# speedup vs baseline: 1.0049x; 1.0049x over previous
; __device__ __forceinline__ float bflo(unsigned w) { return __uint_as_float(w << 16); }
; __device__ __forceinline__ float bfhi(unsigned w) { return __uint_as_float(w & 0xffff0000u); }
; __device__ __forceinline__ void resid_rows(bf16_t* R, const bf16_t* Y, const float* ssqY, const float* g, float* rstd_out, float* outf, bool wf32, int row_lo, int row_hi, int yoff, int gw, int NGW, int lane) {
;     constexpr int RP = 4;
;     f32x4 gv[2][2];
; #pragma unroll
;     for (int j = 0; j < 2; ++j) { gv[j][0] = *(const f32x4*)(g + 8 * lane + 512 * j); gv[j][1] = *(const f32x4*)(g + 8 * lane + 512 * j + 4); }
;     for (int row0 = row_lo + gw; row0 < row_hi; row0 += RP * NGW) {
;         u32x4 rr[RP][2], oo[RP][2]; float ssv[RP];
; #pragma unroll
;         for (int k = 0; k < RP; ++k) { const int row = row0 + k * NGW; const bool ok = row < row_hi; const int rw = ok ? row : row0;
;             ssv[k] = ssqY[rw];
; #pragma unroll
;             for (int j = 0; j < 2; ++j) { const int c = 8 * lane + 512 * j; rr[k][j] = *(const u32x4*)(R + (size_t)rw * DM + c); oo[k][j] = *(const u32x4*)(Y + (size_t)(rw - yoff) * DM + c); } }
; #pragma unroll
;         for (int k = 0; k < RP; ++k) { const int row = row0 + k * NGW; if (row < row_hi) {
;             const float rs = __builtin_amdgcn_rsqf(ssv[k] * (1.0f / DM) + RMS_EPS); float s = 0.f;
; #pragma unroll
;             for (int j = 0; j < 2; ++j) { const int c = 8 * lane + 512 * j; const u32x4 r = rr[k][j], o = oo[k][j]; const f32x4 ga = gv[j][0], gb = gv[j][1];
;                 f32x4 ya, yb; ya[0] = bflo(r.x) + bflo(o.x) * rs * ga[0]; ya[1] = bfhi(r.x) + bfhi(o.x) * rs * ga[1]; ya[2] = bflo(r.y) + bflo(o.y) * rs * ga[2]; ya[3] = bfhi(r.y) + bfhi(o.y) * rs * ga[3];
;                 yb[0] = bflo(r.z) + bflo(o.z) * rs * gb[0]; yb[1] = bfhi(r.z) + bfhi(o.z) * rs * gb[1]; yb[2] = bflo(r.w) + bflo(o.w) * rs * gb[2]; yb[3] = bfhi(r.w) + bfhi(o.w) * rs * gb[3];
;                 if (wf32) { *(f32x4*)(outf + (size_t)row * DM + c) = ya; *(f32x4*)(outf + (size_t)row * DM + c + 4) = yb; }
;                 s += (ya[0] * ya[0] + ya[1] * ya[1]) + (ya[2] * ya[2] + ya[3] * ya[3]) + (yb[0] * yb[0] + yb[1] * yb[1]) + (yb[2] * yb[2] + yb[3] * yb[3]);
;                 u32x4 w; w.x = pk2(ya[0], ya[1]); w.y = pk2(ya[2], ya[3]); w.z = pk2(yb[0], yb[1]); w.w = pk2(yb[2], yb[3]); *(u32x4*)(R + (size_t)row * DM + c) = w; }
.Lrs2_last1:
	v_lshrrev_b32_e32 v114, 6, v0
	v_readlane_b32 s12, v255, 49
	v_readlane_b32 s13, v255, 4
	v_readfirstlane_b32 s18, v114
	s_load_dwordx2 s[4:5], s[0:1], 0x98
	s_load_dwordx2 s[10:11], s[0:1], 0x68
	s_load_dwordx2 s[6:7], s[0:1], 0x90
	s_add_i32 s13, s13, s18
	v_and_b32_e32 v115, 63, v0
	v_lshlrev_b32_e32 v114, 4, v115
	v_lshlrev_b32_e32 v115, 5, v115
	s_lshl_b32 s18, s12, 12
	s_lshl_b32 s19, s12, 18
	s_bfm_b64 s[8:9], 1, 63
	s_waitcnt lgkmcnt(0)
	s_add_u32 s10, s10, s18
	s_addc_u32 s11, s11, 0
	global_load_dwordx4 v[2:5], v115, s[10:11] offset:2048
	global_load_dwordx4 v[6:9], v115, s[10:11] offset:2064
	global_load_dwordx4 v[10:13], v115, s[10:11]
	global_load_dwordx4 v[14:17], v115, s[10:11] offset:16
	s_lshl_b32 s18, s13, 11
	v_add_u32_e32 v18, s18, v114
	v_mov_b32_e32 v19, v18
	v_mov_b32_e32 v20, v18
	s_lshl_b32 s18, s13, 2
	v_mov_b32_e32 v22, s18
	s_add_i32 s18, s18, s19
	v_mov_b32_e32 v21, s18
	s_lshl_b32 s18, s13, 12
	v_add_u32_e32 v23, s18, v115
	v_add_u32_e32 v18, 0x5001000, v18
	s_lshl_b32 s18, s13, 11
	v_add_u32_e32 v18, s18, v18
	s_lshl_b32 s18, s13, 11
	v_add_u32_e32 v20, s18, v20
	v_add_u32_e32 v21, 0x2d70000, v21
	s_lshl_b32 s18, s13, 2
	v_add_u32_e32 v21, s18, v21
	global_load_dwordx4 v[24:27], v18, s[4:5]
	global_load_dwordx4 v[32:35], v20, s[6:7]
	global_load_dwordx4 v[28:31], v18, s[4:5] offset:1024
	global_load_dwordx4 v[36:39], v20, s[6:7] offset:1024
	global_load_dword v40, v21, s[4:5]
	v_add_u32_e32 v18, 0x800, v18
	v_add_u32_e32 v20, 0x800, v20
	v_add_u32_e32 v21, 0x4, v21
	global_load_dwordx4 v[42:45], v18, s[4:5]
	global_load_dwordx4 v[50:53], v20, s[6:7]
	global_load_dwordx4 v[46:49], v18, s[4:5] offset:1024
	global_load_dwordx4 v[54:57], v20, s[6:7] offset:1024
	global_load_dword v58, v21, s[4:5]
	v_add_u32_e32 v18, 0x7ff800, v18
	v_add_u32_e32 v20, 0x7ff800, v20
	v_add_u32_e32 v21, 0x3ffc, v21
	global_load_dwordx4 v[60:63], v18, s[4:5]
	global_load_dwordx4 v[68:71], v20, s[6:7]
	global_load_dwordx4 v[64:67], v18, s[4:5] offset:1024
	global_load_dwordx4 v[72:75], v20, s[6:7] offset:1024
	global_load_dword v76, v21, s[4:5]
	v_add_u32_e32 v18, 0x800, v18
	v_add_u32_e32 v20, 0x800, v20
	v_add_u32_e32 v21, 0x4, v21
	global_load_dwordx4 v[78:81], v18, s[4:5]
	global_load_dwordx4 v[86:89], v20, s[6:7]
	global_load_dwordx4 v[82:85], v18, s[4:5] offset:1024
	global_load_dwordx4 v[90:93], v20, s[6:7] offset:1024
	global_load_dword v94, v21, s[4:5]
	s_waitcnt vmcnt(15)
	v_fmamk_f32 v96, v40, 0x3a800000, v244
	v_rsq_f32_e32 v96, v96
	v_add_u32_e32 v23, 0x4000000, v23
	s_lshl_b32 s18, s13, 12
	v_add_u32_e32 v23, s18, v23
	v_lshlrev_b32_e32 v106, 16, v32
	v_and_b32_e32 v107, 0xffff0000, v32
	v_lshlrev_b32_e32 v108, 16, v24
	v_and_b32_e32 v109, 0xffff0000, v24
	v_pk_mul_f32 v[106:107], v[96:97], v[106:107] op_sel_hi:[0,1]
	v_pk_fma_f32 v[98:99], v[10:11], v[106:107], v[108:109]
	v_lshlrev_b32_e32 v106, 16, v33
	v_and_b32_e32 v107, 0xffff0000, v33
	v_lshlrev_b32_e32 v108, 16, v25
	v_and_b32_e32 v109, 0xffff0000, v25
	v_pk_mul_f32 v[106:107], v[96:97], v[106:107] op_sel_hi:[0,1]
	v_pk_fma_f32 v[100:101], v[12:13], v[106:107], v[108:109]
	v_lshlrev_b32_e32 v106, 16, v34
	v_and_b32_e32 v107, 0xffff0000, v34
	v_lshlrev_b32_e32 v108, 16, v26
	v_and_b32_e32 v109, 0xffff0000, v26
	v_pk_mul_f32 v[106:107], v[96:97], v[106:107] op_sel_hi:[0,1]
	v_pk_fma_f32 v[102:103], v[14:15], v[106:107], v[108:109]
	v_lshlrev_b32_e32 v106, 16, v35
	v_and_b32_e32 v107, 0xffff0000, v35
	v_lshlrev_b32_e32 v108, 16, v27
	v_and_b32_e32 v109, 0xffff0000, v27
	v_pk_mul_f32 v[106:107], v[96:97], v[106:107] op_sel_hi:[0,1]
	v_pk_fma_f32 v[104:105], v[16:17], v[106:107], v[108:109]
	global_store_dwordx4 v23, v[98:101], s[6:7]
	global_store_dwordx4 v23, v[102:105], s[6:7] offset:16
	v_lshlrev_b32_e32 v106, 16, v36
	v_and_b32_e32 v107, 0xffff0000, v36
	v_lshlrev_b32_e32 v108, 16, v28
	v_and_b32_e32 v109, 0xffff0000, v28
	v_pk_mul_f32 v[106:107], v[96:97], v[106:107] op_sel_hi:[0,1]
	v_pk_fma_f32 v[98:99], v[2:3], v[106:107], v[108:109]
	v_lshlrev_b32_e32 v106, 16, v37
	v_and_b32_e32 v107, 0xffff0000, v37
	v_lshlrev_b32_e32 v108, 16, v29
	v_and_b32_e32 v109, 0xffff0000, v29
	v_pk_mul_f32 v[106:107], v[96:97], v[106:107] op_sel_hi:[0,1]
	v_pk_fma_f32 v[100:101], v[4:5], v[106:107], v[108:109]
	v_lshlrev_b32_e32 v106, 16, v38
	v_and_b32_e32 v107, 0xffff0000, v38
	v_lshlrev_b32_e32 v108, 16, v30
	v_and_b32_e32 v109, 0xffff0000, v30
	v_pk_mul_f32 v[106:107], v[96:97], v[106:107] op_sel_hi:[0,1]
	v_pk_fma_f32 v[102:103], v[6:7], v[106:107], v[108:109]
	v_lshlrev_b32_e32 v106, 16, v39
	v_and_b32_e32 v107, 0xffff0000, v39
	v_lshlrev_b32_e32 v108, 16, v31
	v_and_b32_e32 v109, 0xffff0000, v31
	v_pk_mul_f32 v[106:107], v[96:97], v[106:107] op_sel_hi:[0,1]
	v_pk_fma_f32 v[104:105], v[8:9], v[106:107], v[108:109]
	global_store_dwordx4 v23, v[98:101], s[6:7] offset:2048
	global_store_dwordx4 v23, v[102:105], s[6:7] offset:2064
	v_add_u32_e32 v18, 0x7ff800, v18
	v_add_u32_e32 v20, 0x7ff800, v20
	v_add_u32_e32 v21, 0x3ffc, v21
	global_load_dwordx4 v[24:27], v18, s[4:5]
	global_load_dwordx4 v[32:35], v20, s[6:7]
	global_load_dwordx4 v[28:31], v18, s[4:5] offset:1024
	global_load_dwordx4 v[36:39], v20, s[6:7] offset:1024
	global_load_dword v40, v21, s[4:5]
	s_waitcnt vmcnt(19)
; __device__ __forceinline__ float bflo(unsigned w) { return __uint_as_float(w << 16); }
; __device__ __forceinline__ float bfhi(unsigned w) { return __uint_as_float(w & 0xffff0000u); }
; __device__ __forceinline__ void resid_rows(bf16_t* R, const bf16_t* Y, const float* ssqY, const float* g, float* rstd_out, float* outf, bool wf32, int row_lo, int row_hi, int yoff, int gw, int NGW, int lane) {
;     ...
;         for (int k = 0; k < RP; ++k) { const int row = row0 + k * NGW; const bool ok = row < row_hi; const int rw = ok ? row : row0;
;             ssv[k] = ssqY[rw];
; #pragma unroll
;             for (int j = 0; j < 2; ++j) { const int c = 8 * lane + 512 * j; rr[k][j] = *(const u32x4*)(R + (size_t)rw * DM + c); oo[k][j] = *(const u32x4*)(Y + (size_t)(rw - yoff) * DM + c); } }
; #pragma unroll
;         for (int k = 0; k < RP; ++k) { const int row = row0 + k * NGW; if (row < row_hi) {
;             const float rs = __builtin_amdgcn_rsqf(ssv[k] * (1.0f / DM) + RMS_EPS); float s = 0.f;
; #pragma unroll
;             for (int j = 0; j < 2; ++j) { const int c = 8 * lane + 512 * j; const u32x4 r = rr[k][j], o = oo[k][j]; const f32x4 ga = gv[j][0], gb = gv[j][1];
;                 f32x4 ya, yb; ya[0] = bflo(r.x) + bflo(o.x) * rs * ga[0]; ya[1] = bfhi(r.x) + bfhi(o.x) * rs * ga[1]; ya[2] = bflo(r.y) + bflo(o.y) * rs * ga[2]; ya[3] = bfhi(r.y) + bfhi(o.y) * rs * ga[3];
;                 yb[0] = bflo(r.z) + bflo(o.z) * rs * gb[0]; yb[1] = bfhi(r.z) + bfhi(o.z) * rs * gb[1]; yb[2] = bflo(r.w) + bflo(o.w) * rs * gb[2]; yb[3] = bfhi(r.w) + bfhi(o.w) * rs * gb[3];
;                 if (wf32) { *(f32x4*)(outf + (size_t)row * DM + c) = ya; *(f32x4*)(outf + (size_t)row * DM + c + 4) = yb; }
;                 s += (ya[0] * ya[0] + ya[1] * ya[1]) + (ya[2] * ya[2] + ya[3] * ya[3]) + (yb[0] * yb[0] + yb[1] * yb[1]) + (yb[2] * yb[2] + yb[3] * yb[3]);
;                 u32x4 w; w.x = pk2(ya[0], ya[1]); w.y = pk2(ya[2], ya[3]); w.z = pk2(yb[0], yb[1]); w.w = pk2(yb[2], yb[3]); *(u32x4*)(R + (size_t)row * DM + c) = w; }
	v_fmamk_f32 v96, v58, 0x3a800000, v244
	v_rsq_f32_e32 v96, v96
	v_add_u32_e32 v23, 0x1000, v23
	v_lshlrev_b32_e32 v106, 16, v50
	v_and_b32_e32 v107, 0xffff0000, v50
	v_lshlrev_b32_e32 v108, 16, v42
	v_and_b32_e32 v109, 0xffff0000, v42
	v_pk_mul_f32 v[106:107], v[96:97], v[106:107] op_sel_hi:[0,1]
	v_pk_fma_f32 v[98:99], v[10:11], v[106:107], v[108:109]
	v_lshlrev_b32_e32 v106, 16, v51
	v_and_b32_e32 v107, 0xffff0000, v51
	v_lshlrev_b32_e32 v108, 16, v43
	v_and_b32_e32 v109, 0xffff0000, v43
	v_pk_mul_f32 v[106:107], v[96:97], v[106:107] op_sel_hi:[0,1]
	v_pk_fma_f32 v[100:101], v[12:13], v[106:107], v[108:109]
	v_lshlrev_b32_e32 v106, 16, v52
	v_and_b32_e32 v107, 0xffff0000, v52
	v_lshlrev_b32_e32 v108, 16, v44
	v_and_b32_e32 v109, 0xffff0000, v44
	v_pk_mul_f32 v[106:107], v[96:97], v[106:107] op_sel_hi:[0,1]
	v_pk_fma_f32 v[102:103], v[14:15], v[106:107], v[108:109]
	v_lshlrev_b32_e32 v106, 16, v53
	v_and_b32_e32 v107, 0xffff0000, v53
	v_lshlrev_b32_e32 v108, 16, v45
	v_and_b32_e32 v109, 0xffff0000, v45
	v_pk_mul_f32 v[106:107], v[96:97], v[106:107] op_sel_hi:[0,1]
	v_pk_fma_f32 v[104:105], v[16:17], v[106:107], v[108:109]
	global_store_dwordx4 v23, v[98:101], s[6:7]
	global_store_dwordx4 v23, v[102:105], s[6:7] offset:16
	v_lshlrev_b32_e32 v106, 16, v54
	v_and_b32_e32 v107, 0xffff0000, v54
	v_lshlrev_b32_e32 v108, 16, v46
	v_and_b32_e32 v109, 0xffff0000, v46
	v_pk_mul_f32 v[106:107], v[96:97], v[106:107] op_sel_hi:[0,1]
	v_pk_fma_f32 v[98:99], v[2:3], v[106:107], v[108:109]
	v_lshlrev_b32_e32 v106, 16, v55
	v_and_b32_e32 v107, 0xffff0000, v55
	v_lshlrev_b32_e32 v108, 16, v47
	v_and_b32_e32 v109, 0xffff0000, v47
	v_pk_mul_f32 v[106:107], v[96:97], v[106:107] op_sel_hi:[0,1]
	v_pk_fma_f32 v[100:101], v[4:5], v[106:107], v[108:109]
	v_lshlrev_b32_e32 v106, 16, v56
	v_and_b32_e32 v107, 0xffff0000, v56
	v_lshlrev_b32_e32 v108, 16, v48
	v_and_b32_e32 v109, 0xffff0000, v48
	v_pk_mul_f32 v[106:107], v[96:97], v[106:107] op_sel_hi:[0,1]
	v_pk_fma_f32 v[102:103], v[6:7], v[106:107], v[108:109]
	v_lshlrev_b32_e32 v106, 16, v57
	v_and_b32_e32 v107, 0xffff0000, v57
	v_lshlrev_b32_e32 v108, 16, v49
	v_and_b32_e32 v109, 0xffff0000, v49
	v_pk_mul_f32 v[106:107], v[96:97], v[106:107] op_sel_hi:[0,1]
	v_pk_fma_f32 v[104:105], v[8:9], v[106:107], v[108:109]
	global_store_dwordx4 v23, v[98:101], s[6:7] offset:2048
	global_store_dwordx4 v23, v[102:105], s[6:7] offset:2064
	v_add_u32_e32 v18, 0x800, v18
	v_add_u32_e32 v20, 0x800, v20
	v_add_u32_e32 v21, 0x4, v21
	global_load_dwordx4 v[42:45], v18, s[4:5]
	global_load_dwordx4 v[50:53], v20, s[6:7]
	global_load_dwordx4 v[46:49], v18, s[4:5] offset:1024
	global_load_dwordx4 v[54:57], v20, s[6:7] offset:1024
	global_load_dword v58, v21, s[4:5]
	s_waitcnt vmcnt(23)
	v_fmamk_f32 v96, v76, 0x3a800000, v244
	v_rsq_f32_e32 v96, v96
	v_add_u32_e32 v23, 0xfff000, v23
	v_lshlrev_b32_e32 v106, 16, v68
	v_and_b32_e32 v107, 0xffff0000, v68
	v_lshlrev_b32_e32 v108, 16, v60
	v_and_b32_e32 v109, 0xffff0000, v60
	v_pk_mul_f32 v[106:107], v[96:97], v[106:107] op_sel_hi:[0,1]
	v_pk_fma_f32 v[98:99], v[10:11], v[106:107], v[108:109]
	v_lshlrev_b32_e32 v106, 16, v69
	v_and_b32_e32 v107, 0xffff0000, v69
	v_lshlrev_b32_e32 v108, 16, v61
	v_and_b32_e32 v109, 0xffff0000, v61
	v_pk_mul_f32 v[106:107], v[96:97], v[106:107] op_sel_hi:[0,1]
	v_pk_fma_f32 v[100:101], v[12:13], v[106:107], v[108:109]
	v_lshlrev_b32_e32 v106, 16, v70
	v_and_b32_e32 v107, 0xffff0000, v70
	v_lshlrev_b32_e32 v108, 16, v62
	v_and_b32_e32 v109, 0xffff0000, v62
	v_pk_mul_f32 v[106:107], v[96:97], v[106:107] op_sel_hi:[0,1]
	v_pk_fma_f32 v[102:103], v[14:15], v[106:107], v[108:109]
	v_lshlrev_b32_e32 v106, 16, v71
	v_and_b32_e32 v107, 0xffff0000, v71
	v_lshlrev_b32_e32 v108, 16, v63
	v_and_b32_e32 v109, 0xffff0000, v63
	v_pk_mul_f32 v[106:107], v[96:97], v[106:107] op_sel_hi:[0,1]
	v_pk_fma_f32 v[104:105], v[16:17], v[106:107], v[108:109]
	global_store_dwordx4 v23, v[98:101], s[6:7]
	global_store_dwordx4 v23, v[102:105], s[6:7] offset:16
	v_lshlrev_b32_e32 v106, 16, v72
	v_and_b32_e32 v107, 0xffff0000, v72
	v_lshlrev_b32_e32 v108, 16, v64
	v_and_b32_e32 v109, 0xffff0000, v64
	v_pk_mul_f32 v[106:107], v[96:97], v[106:107] op_sel_hi:[0,1]
	v_pk_fma_f32 v[98:99], v[2:3], v[106:107], v[108:109]
	v_lshlrev_b32_e32 v106, 16, v73
	v_and_b32_e32 v107, 0xffff0000, v73
	v_lshlrev_b32_e32 v108, 16, v65
	v_and_b32_e32 v109, 0xffff0000, v65
	v_pk_mul_f32 v[106:107], v[96:97], v[106:107] op_sel_hi:[0,1]
	v_pk_fma_f32 v[100:101], v[4:5], v[106:107], v[108:109]
	v_lshlrev_b32_e32 v106, 16, v74
	v_and_b32_e32 v107, 0xffff0000, v74
	v_lshlrev_b32_e32 v108, 16, v66
	v_and_b32_e32 v109, 0xffff0000, v66
	v_pk_mul_f32 v[106:107], v[96:97], v[106:107] op_sel_hi:[0,1]
	v_pk_fma_f32 v[102:103], v[6:7], v[106:107], v[108:109]
	v_lshlrev_b32_e32 v106, 16, v75
	v_and_b32_e32 v107, 0xffff0000, v75
	v_lshlrev_b32_e32 v108, 16, v67
	v_and_b32_e32 v109, 0xffff0000, v67
	v_pk_mul_f32 v[106:107], v[96:97], v[106:107] op_sel_hi:[0,1]
	v_pk_fma_f32 v[104:105], v[8:9], v[106:107], v[108:109]
	global_store_dwordx4 v23, v[98:101], s[6:7] offset:2048
	global_store_dwordx4 v23, v[102:105], s[6:7] offset:2064
	v_add_u32_e32 v18, 0x7ff800, v18
	v_add_u32_e32 v20, 0x7ff800, v20
	v_add_u32_e32 v21, 0x3ffc, v21
	global_load_dwordx4 v[60:63], v18, s[4:5]
	global_load_dwordx4 v[68:71], v20, s[6:7]
	global_load_dwordx4 v[64:67], v18, s[4:5] offset:1024
	global_load_dwordx4 v[72:75], v20, s[6:7] offset:1024
	global_load_dword v76, v21, s[4:5]
	s_waitcnt vmcnt(27)
; __device__ __forceinline__ float bflo(unsigned w) { return __uint_as_float(w << 16); }
; __device__ __forceinline__ float bfhi(unsigned w) { return __uint_as_float(w & 0xffff0000u); }
; __device__ __forceinline__ void resid_rows(bf16_t* R, const bf16_t* Y, const float* ssqY, const float* g, float* rstd_out, float* outf, bool wf32, int row_lo, int row_hi, int yoff, int gw, int NGW, int lane) {
;     ...
;         for (int k = 0; k < RP; ++k) { const int row = row0 + k * NGW; const bool ok = row < row_hi; const int rw = ok ? row : row0;
;             ssv[k] = ssqY[rw];
; #pragma unroll
;             for (int j = 0; j < 2; ++j) { const int c = 8 * lane + 512 * j; rr[k][j] = *(const u32x4*)(R + (size_t)rw * DM + c); oo[k][j] = *(const u32x4*)(Y + (size_t)(rw - yoff) * DM + c); } }
; #pragma unroll
;         for (int k = 0; k < RP; ++k) { const int row = row0 + k * NGW; if (row < row_hi) {
;             const float rs = __builtin_amdgcn_rsqf(ssv[k] * (1.0f / DM) + RMS_EPS); float s = 0.f;
; #pragma unroll
;             for (int j = 0; j < 2; ++j) { const int c = 8 * lane + 512 * j; const u32x4 r = rr[k][j], o = oo[k][j]; const f32x4 ga = gv[j][0], gb = gv[j][1];
;                 f32x4 ya, yb; ya[0] = bflo(r.x) + bflo(o.x) * rs * ga[0]; ya[1] = bfhi(r.x) + bfhi(o.x) * rs * ga[1]; ya[2] = bflo(r.y) + bflo(o.y) * rs * ga[2]; ya[3] = bfhi(r.y) + bfhi(o.y) * rs * ga[3];
;                 yb[0] = bflo(r.z) + bflo(o.z) * rs * gb[0]; yb[1] = bfhi(r.z) + bfhi(o.z) * rs * gb[1]; yb[2] = bflo(r.w) + bflo(o.w) * rs * gb[2]; yb[3] = bfhi(r.w) + bfhi(o.w) * rs * gb[3];
;                 if (wf32) { *(f32x4*)(outf + (size_t)row * DM + c) = ya; *(f32x4*)(outf + (size_t)row * DM + c + 4) = yb; }
;                 s += (ya[0] * ya[0] + ya[1] * ya[1]) + (ya[2] * ya[2] + ya[3] * ya[3]) + (yb[0] * yb[0] + yb[1] * yb[1]) + (yb[2] * yb[2] + yb[3] * yb[3]);
;                 u32x4 w; w.x = pk2(ya[0], ya[1]); w.y = pk2(ya[2], ya[3]); w.z = pk2(yb[0], yb[1]); w.w = pk2(yb[2], yb[3]); *(u32x4*)(R + (size_t)row * DM + c) = w; }
	v_fmamk_f32 v96, v94, 0x3a800000, v244
	v_rsq_f32_e32 v96, v96
	v_add_u32_e32 v23, 0x1000, v23
	v_lshlrev_b32_e32 v106, 16, v86
	v_and_b32_e32 v107, 0xffff0000, v86
	v_lshlrev_b32_e32 v108, 16, v78
	v_and_b32_e32 v109, 0xffff0000, v78
	v_pk_mul_f32 v[106:107], v[96:97], v[106:107] op_sel_hi:[0,1]
	v_pk_fma_f32 v[98:99], v[10:11], v[106:107], v[108:109]
	v_lshlrev_b32_e32 v106, 16, v87
	v_and_b32_e32 v107, 0xffff0000, v87
	v_lshlrev_b32_e32 v108, 16, v79
	v_and_b32_e32 v109, 0xffff0000, v79
	v_pk_mul_f32 v[106:107], v[96:97], v[106:107] op_sel_hi:[0,1]
	v_pk_fma_f32 v[100:101], v[12:13], v[106:107], v[108:109]
	v_lshlrev_b32_e32 v106, 16, v88
	v_and_b32_e32 v107, 0xffff0000, v88
	v_lshlrev_b32_e32 v108, 16, v80
	v_and_b32_e32 v109, 0xffff0000, v80
	v_pk_mul_f32 v[106:107], v[96:97], v[106:107] op_sel_hi:[0,1]
	v_pk_fma_f32 v[102:103], v[14:15], v[106:107], v[108:109]
	v_lshlrev_b32_e32 v106, 16, v89
	v_and_b32_e32 v107, 0xffff0000, v89
	v_lshlrev_b32_e32 v108, 16, v81
	v_and_b32_e32 v109, 0xffff0000, v81
	v_pk_mul_f32 v[106:107], v[96:97], v[106:107] op_sel_hi:[0,1]
	v_pk_fma_f32 v[104:105], v[16:17], v[106:107], v[108:109]
	global_store_dwordx4 v23, v[98:101], s[6:7]
	global_store_dwordx4 v23, v[102:105], s[6:7] offset:16
	v_lshlrev_b32_e32 v106, 16, v90
	v_and_b32_e32 v107, 0xffff0000, v90
	v_lshlrev_b32_e32 v108, 16, v82
	v_and_b32_e32 v109, 0xffff0000, v82
	v_pk_mul_f32 v[106:107], v[96:97], v[106:107] op_sel_hi:[0,1]
	v_pk_fma_f32 v[98:99], v[2:3], v[106:107], v[108:109]
	v_lshlrev_b32_e32 v106, 16, v91
	v_and_b32_e32 v107, 0xffff0000, v91
	v_lshlrev_b32_e32 v108, 16, v83
	v_and_b32_e32 v109, 0xffff0000, v83
	v_pk_mul_f32 v[106:107], v[96:97], v[106:107] op_sel_hi:[0,1]
	v_pk_fma_f32 v[100:101], v[4:5], v[106:107], v[108:109]
	v_lshlrev_b32_e32 v106, 16, v92
	v_and_b32_e32 v107, 0xffff0000, v92
	v_lshlrev_b32_e32 v108, 16, v84
	v_and_b32_e32 v109, 0xffff0000, v84
	v_pk_mul_f32 v[106:107], v[96:97], v[106:107] op_sel_hi:[0,1]
	v_pk_fma_f32 v[102:103], v[6:7], v[106:107], v[108:109]
	v_lshlrev_b32_e32 v106, 16, v93
	v_and_b32_e32 v107, 0xffff0000, v93
	v_lshlrev_b32_e32 v108, 16, v85
	v_and_b32_e32 v109, 0xffff0000, v85
	v_pk_mul_f32 v[106:107], v[96:97], v[106:107] op_sel_hi:[0,1]
	v_pk_fma_f32 v[104:105], v[8:9], v[106:107], v[108:109]
	global_store_dwordx4 v23, v[98:101], s[6:7] offset:2048
	global_store_dwordx4 v23, v[102:105], s[6:7] offset:2064
	v_add_u32_e32 v18, 0x800, v18
	v_add_u32_e32 v20, 0x800, v20
	v_add_u32_e32 v21, 0x4, v21
	global_load_dwordx4 v[78:81], v18, s[4:5]
	global_load_dwordx4 v[86:89], v20, s[6:7]
	global_load_dwordx4 v[82:85], v18, s[4:5] offset:1024
	global_load_dwordx4 v[90:93], v20, s[6:7] offset:1024
	global_load_dword v94, v21, s[4:5]
	s_waitcnt vmcnt(27)
	v_fmamk_f32 v96, v40, 0x3a800000, v244
	v_rsq_f32_e32 v96, v96
	v_add_u32_e32 v23, 0xfff000, v23
	v_lshlrev_b32_e32 v106, 16, v32
	v_and_b32_e32 v107, 0xffff0000, v32
	v_lshlrev_b32_e32 v108, 16, v24
	v_and_b32_e32 v109, 0xffff0000, v24
	v_pk_mul_f32 v[106:107], v[96:97], v[106:107] op_sel_hi:[0,1]
	v_pk_fma_f32 v[98:99], v[10:11], v[106:107], v[108:109]
	v_lshlrev_b32_e32 v106, 16, v33
	v_and_b32_e32 v107, 0xffff0000, v33
	v_lshlrev_b32_e32 v108, 16, v25
	v_and_b32_e32 v109, 0xffff0000, v25
	v_pk_mul_f32 v[106:107], v[96:97], v[106:107] op_sel_hi:[0,1]
	v_pk_fma_f32 v[100:101], v[12:13], v[106:107], v[108:109]
	v_lshlrev_b32_e32 v106, 16, v34
	v_and_b32_e32 v107, 0xffff0000, v34
	v_lshlrev_b32_e32 v108, 16, v26
	v_and_b32_e32 v109, 0xffff0000, v26
	v_pk_mul_f32 v[106:107], v[96:97], v[106:107] op_sel_hi:[0,1]
	v_pk_fma_f32 v[102:103], v[14:15], v[106:107], v[108:109]
	v_lshlrev_b32_e32 v106, 16, v35
	v_and_b32_e32 v107, 0xffff0000, v35
	v_lshlrev_b32_e32 v108, 16, v27
	v_and_b32_e32 v109, 0xffff0000, v27
	v_pk_mul_f32 v[106:107], v[96:97], v[106:107] op_sel_hi:[0,1]
	v_pk_fma_f32 v[104:105], v[16:17], v[106:107], v[108:109]
	global_store_dwordx4 v23, v[98:101], s[6:7]
	global_store_dwordx4 v23, v[102:105], s[6:7] offset:16
	v_lshlrev_b32_e32 v106, 16, v36
	v_and_b32_e32 v107, 0xffff0000, v36
	v_lshlrev_b32_e32 v108, 16, v28
	v_and_b32_e32 v109, 0xffff0000, v28
	v_pk_mul_f32 v[106:107], v[96:97], v[106:107] op_sel_hi:[0,1]
	v_pk_fma_f32 v[98:99], v[2:3], v[106:107], v[108:109]
	v_lshlrev_b32_e32 v106, 16, v37
	v_and_b32_e32 v107, 0xffff0000, v37
	v_lshlrev_b32_e32 v108, 16, v29
	v_and_b32_e32 v109, 0xffff0000, v29
	v_pk_mul_f32 v[106:107], v[96:97], v[106:107] op_sel_hi:[0,1]
	v_pk_fma_f32 v[100:101], v[4:5], v[106:107], v[108:109]
	v_lshlrev_b32_e32 v106, 16, v38
	v_and_b32_e32 v107, 0xffff0000, v38
	v_lshlrev_b32_e32 v108, 16, v30
	v_and_b32_e32 v109, 0xffff0000, v30
	v_pk_mul_f32 v[106:107], v[96:97], v[106:107] op_sel_hi:[0,1]
	v_pk_fma_f32 v[102:103], v[6:7], v[106:107], v[108:109]
	v_lshlrev_b32_e32 v106, 16, v39
	v_and_b32_e32 v107, 0xffff0000, v39
	v_lshlrev_b32_e32 v108, 16, v31
	v_and_b32_e32 v109, 0xffff0000, v31
	v_pk_mul_f32 v[106:107], v[96:97], v[106:107] op_sel_hi:[0,1]
	v_pk_fma_f32 v[104:105], v[8:9], v[106:107], v[108:109]
	global_store_dwordx4 v23, v[98:101], s[6:7] offset:2048
	global_store_dwordx4 v23, v[102:105], s[6:7] offset:2064
	v_add_u32_e32 v18, 0xfc7ff800, v18
	s_lshl_b32 s18, s13, 11
	v_subrev_u32_e32 v18, s18, v18
	v_add_u32_e32 v20, 0xb7ff800, v20
	s_lshl_b32 s18, s13, 11
	v_subrev_u32_e32 v20, s18, v20
	v_add_u32_e32 v21, 0xfffe3ffc, v21
	s_lshl_b32 s18, s13, 2
	v_subrev_u32_e32 v21, s18, v21
	global_load_dwordx4 v[24:27], v18, s[4:5]
	global_load_dwordx4 v[32:35], v20, s[4:5]
	global_load_dwordx4 v[28:31], v18, s[4:5] offset:1024
	global_load_dwordx4 v[36:39], v20, s[4:5] offset:1024
	global_load_dword v40, v21, s[4:5]
	s_waitcnt vmcnt(27)
; __device__ __forceinline__ float bflo(unsigned w) { return __uint_as_float(w << 16); }
; __device__ __forceinline__ float bfhi(unsigned w) { return __uint_as_float(w & 0xffff0000u); }
; __device__ __forceinline__ void resid_rows(bf16_t* R, const bf16_t* Y, const float* ssqY, const float* g, float* rstd_out, float* outf, bool wf32, int row_lo, int row_hi, int yoff, int gw, int NGW, int lane) {
;     ...
;         for (int k = 0; k < RP; ++k) { const int row = row0 + k * NGW; const bool ok = row < row_hi; const int rw = ok ? row : row0;
;             ssv[k] = ssqY[rw];
; #pragma unroll
;             for (int j = 0; j < 2; ++j) { const int c = 8 * lane + 512 * j; rr[k][j] = *(const u32x4*)(R + (size_t)rw * DM + c); oo[k][j] = *(const u32x4*)(Y + (size_t)(rw - yoff) * DM + c); } }
; #pragma unroll
;         for (int k = 0; k < RP; ++k) { const int row = row0 + k * NGW; if (row < row_hi) {
;             const float rs = __builtin_amdgcn_rsqf(ssv[k] * (1.0f / DM) + RMS_EPS); float s = 0.f;
; #pragma unroll
;             for (int j = 0; j < 2; ++j) { const int c = 8 * lane + 512 * j; const u32x4 r = rr[k][j], o = oo[k][j]; const f32x4 ga = gv[j][0], gb = gv[j][1];
;                 f32x4 ya, yb; ya[0] = bflo(r.x) + bflo(o.x) * rs * ga[0]; ya[1] = bfhi(r.x) + bfhi(o.x) * rs * ga[1]; ya[2] = bflo(r.y) + bflo(o.y) * rs * ga[2]; ya[3] = bfhi(r.y) + bfhi(o.y) * rs * ga[3];
;                 yb[0] = bflo(r.z) + bflo(o.z) * rs * gb[0]; yb[1] = bfhi(r.z) + bfhi(o.z) * rs * gb[1]; yb[2] = bflo(r.w) + bflo(o.w) * rs * gb[2]; yb[3] = bfhi(r.w) + bfhi(o.w) * rs * gb[3];
;                 if (wf32) { *(f32x4*)(outf + (size_t)row * DM + c) = ya; *(f32x4*)(outf + (size_t)row * DM + c + 4) = yb; }
;                 s += (ya[0] * ya[0] + ya[1] * ya[1]) + (ya[2] * ya[2] + ya[3] * ya[3]) + (yb[0] * yb[0] + yb[1] * yb[1]) + (yb[2] * yb[2] + yb[3] * yb[3]);
;                 u32x4 w; w.x = pk2(ya[0], ya[1]); w.y = pk2(ya[2], ya[3]); w.z = pk2(yb[0], yb[1]); w.w = pk2(yb[2], yb[3]); *(u32x4*)(R + (size_t)row * DM + c) = w; }
	v_fmamk_f32 v96, v58, 0x3a800000, v244
	v_rsq_f32_e32 v96, v96
	v_add_u32_e32 v23, 0x1000, v23
	v_lshlrev_b32_e32 v106, 16, v50
	v_and_b32_e32 v107, 0xffff0000, v50
	v_lshlrev_b32_e32 v108, 16, v42
	v_and_b32_e32 v109, 0xffff0000, v42
	v_pk_mul_f32 v[106:107], v[96:97], v[106:107] op_sel_hi:[0,1]
	v_pk_fma_f32 v[98:99], v[10:11], v[106:107], v[108:109]
	v_lshlrev_b32_e32 v106, 16, v51
	v_and_b32_e32 v107, 0xffff0000, v51
	v_lshlrev_b32_e32 v108, 16, v43
	v_and_b32_e32 v109, 0xffff0000, v43
	v_pk_mul_f32 v[106:107], v[96:97], v[106:107] op_sel_hi:[0,1]
	v_pk_fma_f32 v[100:101], v[12:13], v[106:107], v[108:109]
	v_lshlrev_b32_e32 v106, 16, v52
	v_and_b32_e32 v107, 0xffff0000, v52
	v_lshlrev_b32_e32 v108, 16, v44
	v_and_b32_e32 v109, 0xffff0000, v44
	v_pk_mul_f32 v[106:107], v[96:97], v[106:107] op_sel_hi:[0,1]
	v_pk_fma_f32 v[102:103], v[14:15], v[106:107], v[108:109]
	v_lshlrev_b32_e32 v106, 16, v53
	v_and_b32_e32 v107, 0xffff0000, v53
	v_lshlrev_b32_e32 v108, 16, v45
	v_and_b32_e32 v109, 0xffff0000, v45
	v_pk_mul_f32 v[106:107], v[96:97], v[106:107] op_sel_hi:[0,1]
	v_pk_fma_f32 v[104:105], v[16:17], v[106:107], v[108:109]
	global_store_dwordx4 v23, v[98:101], s[6:7]
	global_store_dwordx4 v23, v[102:105], s[6:7] offset:16
	v_lshlrev_b32_e32 v106, 16, v54
	v_and_b32_e32 v107, 0xffff0000, v54
	v_lshlrev_b32_e32 v108, 16, v46
	v_and_b32_e32 v109, 0xffff0000, v46
	v_pk_mul_f32 v[106:107], v[96:97], v[106:107] op_sel_hi:[0,1]
	v_pk_fma_f32 v[98:99], v[2:3], v[106:107], v[108:109]
	v_lshlrev_b32_e32 v106, 16, v55
	v_and_b32_e32 v107, 0xffff0000, v55
	v_lshlrev_b32_e32 v108, 16, v47
	v_and_b32_e32 v109, 0xffff0000, v47
	v_pk_mul_f32 v[106:107], v[96:97], v[106:107] op_sel_hi:[0,1]
	v_pk_fma_f32 v[100:101], v[4:5], v[106:107], v[108:109]
	v_lshlrev_b32_e32 v106, 16, v56
	v_and_b32_e32 v107, 0xffff0000, v56
	v_lshlrev_b32_e32 v108, 16, v48
	v_and_b32_e32 v109, 0xffff0000, v48
	v_pk_mul_f32 v[106:107], v[96:97], v[106:107] op_sel_hi:[0,1]
	v_pk_fma_f32 v[102:103], v[6:7], v[106:107], v[108:109]
	v_lshlrev_b32_e32 v106, 16, v57
	v_and_b32_e32 v107, 0xffff0000, v57
	v_lshlrev_b32_e32 v108, 16, v49
	v_and_b32_e32 v109, 0xffff0000, v49
	v_pk_mul_f32 v[106:107], v[96:97], v[106:107] op_sel_hi:[0,1]
	v_pk_fma_f32 v[104:105], v[8:9], v[106:107], v[108:109]
	global_store_dwordx4 v23, v[98:101], s[6:7] offset:2048
	global_store_dwordx4 v23, v[102:105], s[6:7] offset:2064
	v_add_u32_e32 v18, 0x400000, v18
	v_add_u32_e32 v20, 0x400000, v20
	v_add_u32_e32 v21, 0x2000, v21
	global_load_dwordx4 v[42:45], v18, s[4:5]
	global_load_dwordx4 v[50:53], v20, s[4:5]
	global_load_dwordx4 v[46:49], v18, s[4:5] offset:1024
	global_load_dwordx4 v[54:57], v20, s[4:5] offset:1024
	global_load_dword v58, v21, s[4:5]
	s_waitcnt vmcnt(27)
	v_fmamk_f32 v96, v76, 0x3a800000, v244
	v_rsq_f32_e32 v96, v96
	v_add_u32_e32 v23, 0xfff000, v23
	v_lshlrev_b32_e32 v106, 16, v68
	v_and_b32_e32 v107, 0xffff0000, v68
	v_lshlrev_b32_e32 v108, 16, v60
	v_and_b32_e32 v109, 0xffff0000, v60
	v_pk_mul_f32 v[106:107], v[96:97], v[106:107] op_sel_hi:[0,1]
	v_pk_fma_f32 v[98:99], v[10:11], v[106:107], v[108:109]
	v_lshlrev_b32_e32 v106, 16, v69
	v_and_b32_e32 v107, 0xffff0000, v69
	v_lshlrev_b32_e32 v108, 16, v61
	v_and_b32_e32 v109, 0xffff0000, v61
	v_pk_mul_f32 v[106:107], v[96:97], v[106:107] op_sel_hi:[0,1]
	v_pk_fma_f32 v[100:101], v[12:13], v[106:107], v[108:109]
	v_lshlrev_b32_e32 v106, 16, v70
	v_and_b32_e32 v107, 0xffff0000, v70
	v_lshlrev_b32_e32 v108, 16, v62
	v_and_b32_e32 v109, 0xffff0000, v62
	v_pk_mul_f32 v[106:107], v[96:97], v[106:107] op_sel_hi:[0,1]
	v_pk_fma_f32 v[102:103], v[14:15], v[106:107], v[108:109]
	v_lshlrev_b32_e32 v106, 16, v71
	v_and_b32_e32 v107, 0xffff0000, v71
	v_lshlrev_b32_e32 v108, 16, v63
	v_and_b32_e32 v109, 0xffff0000, v63
	v_pk_mul_f32 v[106:107], v[96:97], v[106:107] op_sel_hi:[0,1]
	v_pk_fma_f32 v[104:105], v[16:17], v[106:107], v[108:109]
	global_store_dwordx4 v23, v[98:101], s[6:7]
	global_store_dwordx4 v23, v[102:105], s[6:7] offset:16
	v_lshlrev_b32_e32 v106, 16, v72
	v_and_b32_e32 v107, 0xffff0000, v72
	v_lshlrev_b32_e32 v108, 16, v64
	v_and_b32_e32 v109, 0xffff0000, v64
	v_pk_mul_f32 v[106:107], v[96:97], v[106:107] op_sel_hi:[0,1]
	v_pk_fma_f32 v[98:99], v[2:3], v[106:107], v[108:109]
	v_lshlrev_b32_e32 v106, 16, v73
	v_and_b32_e32 v107, 0xffff0000, v73
	v_lshlrev_b32_e32 v108, 16, v65
	v_and_b32_e32 v109, 0xffff0000, v65
	v_pk_mul_f32 v[106:107], v[96:97], v[106:107] op_sel_hi:[0,1]
	v_pk_fma_f32 v[100:101], v[4:5], v[106:107], v[108:109]
	v_lshlrev_b32_e32 v106, 16, v74
	v_and_b32_e32 v107, 0xffff0000, v74
	v_lshlrev_b32_e32 v108, 16, v66
	v_and_b32_e32 v109, 0xffff0000, v66
	v_pk_mul_f32 v[106:107], v[96:97], v[106:107] op_sel_hi:[0,1]
	v_pk_fma_f32 v[102:103], v[6:7], v[106:107], v[108:109]
	v_lshlrev_b32_e32 v106, 16, v75
	v_and_b32_e32 v107, 0xffff0000, v75
	v_lshlrev_b32_e32 v108, 16, v67
	v_and_b32_e32 v109, 0xffff0000, v67
	v_pk_mul_f32 v[106:107], v[96:97], v[106:107] op_sel_hi:[0,1]
	v_pk_fma_f32 v[104:105], v[8:9], v[106:107], v[108:109]
	global_store_dwordx4 v23, v[98:101], s[6:7] offset:2048
	global_store_dwordx4 v23, v[102:105], s[6:7] offset:2064
	v_add_u32_e32 v18, 0x400000, v18
	v_add_u32_e32 v20, 0x400000, v20
	v_add_u32_e32 v21, 0x2000, v21
	global_load_dwordx4 v[60:63], v18, s[4:5]
	global_load_dwordx4 v[68:71], v20, s[4:5]
	global_load_dwordx4 v[64:67], v18, s[4:5] offset:1024
	global_load_dwordx4 v[72:75], v20, s[4:5] offset:1024
	global_load_dword v76, v21, s[4:5]
	s_waitcnt vmcnt(27)
; __device__ __forceinline__ float bflo(unsigned w) { return __uint_as_float(w << 16); }
; __device__ __forceinline__ float bfhi(unsigned w) { return __uint_as_float(w & 0xffff0000u); }
; __device__ __forceinline__ void resid_rows(bf16_t* R, const bf16_t* Y, const float* ssqY, const float* g, float* rstd_out, float* outf, bool wf32, int row_lo, int row_hi, int yoff, int gw, int NGW, int lane) {
;     ...
;         for (int k = 0; k < RP; ++k) { const int row = row0 + k * NGW; const bool ok = row < row_hi; const int rw = ok ? row : row0;
;             ssv[k] = ssqY[rw];
; #pragma unroll
;             for (int j = 0; j < 2; ++j) { const int c = 8 * lane + 512 * j; rr[k][j] = *(const u32x4*)(R + (size_t)rw * DM + c); oo[k][j] = *(const u32x4*)(Y + (size_t)(rw - yoff) * DM + c); } }
; #pragma unroll
;         for (int k = 0; k < RP; ++k) { const int row = row0 + k * NGW; if (row < row_hi) {
;             const float rs = __builtin_amdgcn_rsqf(ssv[k] * (1.0f / DM) + RMS_EPS); float s = 0.f;
; #pragma unroll
;             for (int j = 0; j < 2; ++j) { const int c = 8 * lane + 512 * j; const u32x4 r = rr[k][j], o = oo[k][j]; const f32x4 ga = gv[j][0], gb = gv[j][1];
;                 f32x4 ya, yb; ya[0] = bflo(r.x) + bflo(o.x) * rs * ga[0]; ya[1] = bfhi(r.x) + bfhi(o.x) * rs * ga[1]; ya[2] = bflo(r.y) + bflo(o.y) * rs * ga[2]; ya[3] = bfhi(r.y) + bfhi(o.y) * rs * ga[3];
;                 yb[0] = bflo(r.z) + bflo(o.z) * rs * gb[0]; yb[1] = bfhi(r.z) + bfhi(o.z) * rs * gb[1]; yb[2] = bflo(r.w) + bflo(o.w) * rs * gb[2]; yb[3] = bfhi(r.w) + bfhi(o.w) * rs * gb[3];
;                 if (wf32) { *(f32x4*)(outf + (size_t)row * DM + c) = ya; *(f32x4*)(outf + (size_t)row * DM + c + 4) = yb; }
;                 s += (ya[0] * ya[0] + ya[1] * ya[1]) + (ya[2] * ya[2] + ya[3] * ya[3]) + (yb[0] * yb[0] + yb[1] * yb[1]) + (yb[2] * yb[2] + yb[3] * yb[3]);
;                 u32x4 w; w.x = pk2(ya[0], ya[1]); w.y = pk2(ya[2], ya[3]); w.z = pk2(yb[0], yb[1]); w.w = pk2(yb[2], yb[3]); *(u32x4*)(R + (size_t)row * DM + c) = w; }
	v_fmamk_f32 v96, v94, 0x3a800000, v244
	v_rsq_f32_e32 v96, v96
	v_add_u32_e32 v23, 0x1000, v23
	v_lshlrev_b32_e32 v106, 16, v86
	v_and_b32_e32 v107, 0xffff0000, v86
	v_lshlrev_b32_e32 v108, 16, v78
	v_and_b32_e32 v109, 0xffff0000, v78
	v_pk_mul_f32 v[106:107], v[96:97], v[106:107] op_sel_hi:[0,1]
	v_pk_fma_f32 v[98:99], v[10:11], v[106:107], v[108:109]
	v_lshlrev_b32_e32 v106, 16, v87
	v_and_b32_e32 v107, 0xffff0000, v87
	v_lshlrev_b32_e32 v108, 16, v79
	v_and_b32_e32 v109, 0xffff0000, v79
	v_pk_mul_f32 v[106:107], v[96:97], v[106:107] op_sel_hi:[0,1]
	v_pk_fma_f32 v[100:101], v[12:13], v[106:107], v[108:109]
	v_lshlrev_b32_e32 v106, 16, v88
	v_and_b32_e32 v107, 0xffff0000, v88
	v_lshlrev_b32_e32 v108, 16, v80
	v_and_b32_e32 v109, 0xffff0000, v80
	v_pk_mul_f32 v[106:107], v[96:97], v[106:107] op_sel_hi:[0,1]
	v_pk_fma_f32 v[102:103], v[14:15], v[106:107], v[108:109]
	v_lshlrev_b32_e32 v106, 16, v89
	v_and_b32_e32 v107, 0xffff0000, v89
	v_lshlrev_b32_e32 v108, 16, v81
	v_and_b32_e32 v109, 0xffff0000, v81
	v_pk_mul_f32 v[106:107], v[96:97], v[106:107] op_sel_hi:[0,1]
	v_pk_fma_f32 v[104:105], v[16:17], v[106:107], v[108:109]
	global_store_dwordx4 v23, v[98:101], s[6:7]
	global_store_dwordx4 v23, v[102:105], s[6:7] offset:16
	v_lshlrev_b32_e32 v106, 16, v90
	v_and_b32_e32 v107, 0xffff0000, v90
	v_lshlrev_b32_e32 v108, 16, v82
	v_and_b32_e32 v109, 0xffff0000, v82
	v_pk_mul_f32 v[106:107], v[96:97], v[106:107] op_sel_hi:[0,1]
	v_pk_fma_f32 v[98:99], v[2:3], v[106:107], v[108:109]
	v_lshlrev_b32_e32 v106, 16, v91
	v_and_b32_e32 v107, 0xffff0000, v91
	v_lshlrev_b32_e32 v108, 16, v83
	v_and_b32_e32 v109, 0xffff0000, v83
	v_pk_mul_f32 v[106:107], v[96:97], v[106:107] op_sel_hi:[0,1]
	v_pk_fma_f32 v[100:101], v[4:5], v[106:107], v[108:109]
	v_lshlrev_b32_e32 v106, 16, v92
	v_and_b32_e32 v107, 0xffff0000, v92
	v_lshlrev_b32_e32 v108, 16, v84
	v_and_b32_e32 v109, 0xffff0000, v84
	v_pk_mul_f32 v[106:107], v[96:97], v[106:107] op_sel_hi:[0,1]
	v_pk_fma_f32 v[102:103], v[6:7], v[106:107], v[108:109]
	v_lshlrev_b32_e32 v106, 16, v93
	v_and_b32_e32 v107, 0xffff0000, v93
	v_lshlrev_b32_e32 v108, 16, v85
	v_and_b32_e32 v109, 0xffff0000, v85
	v_pk_mul_f32 v[106:107], v[96:97], v[106:107] op_sel_hi:[0,1]
	v_pk_fma_f32 v[104:105], v[8:9], v[106:107], v[108:109]
	global_store_dwordx4 v23, v[98:101], s[6:7] offset:2048
	global_store_dwordx4 v23, v[102:105], s[6:7] offset:2064
	v_add_u32_e32 v18, 0x400000, v18
	v_add_u32_e32 v20, 0x400000, v20
	v_add_u32_e32 v21, 0x2000, v21
	global_load_dwordx4 v[78:81], v18, s[4:5]
	global_load_dwordx4 v[86:89], v20, s[4:5]
	global_load_dwordx4 v[82:85], v18, s[4:5] offset:1024
	global_load_dwordx4 v[90:93], v20, s[4:5] offset:1024
	global_load_dword v94, v21, s[4:5]
	s_waitcnt vmcnt(27)
	v_fmamk_f32 v96, v40, 0x3a800000, v244
	v_rsq_f32_e32 v96, v96
	v_add_u32_e32 v23, 0xf8fff000, v23
	s_lshl_b32 s18, s13, 12
	v_subrev_u32_e32 v23, s18, v23
	v_lshlrev_b32_e32 v106, 16, v32
	v_and_b32_e32 v107, 0xffff0000, v32
	v_lshlrev_b32_e32 v108, 16, v24
	v_and_b32_e32 v109, 0xffff0000, v24
	v_pk_mul_f32 v[106:107], v[96:97], v[106:107] op_sel_hi:[0,1]
	v_pk_fma_f32 v[98:99], v[10:11], v[106:107], v[108:109]
	v_lshlrev_b32_e32 v106, 16, v33
	v_and_b32_e32 v107, 0xffff0000, v33
	v_lshlrev_b32_e32 v108, 16, v25
	v_and_b32_e32 v109, 0xffff0000, v25
	v_pk_mul_f32 v[106:107], v[96:97], v[106:107] op_sel_hi:[0,1]
	v_pk_fma_f32 v[100:101], v[12:13], v[106:107], v[108:109]
	v_lshlrev_b32_e32 v106, 16, v34
	v_and_b32_e32 v107, 0xffff0000, v34
	v_lshlrev_b32_e32 v108, 16, v26
	v_and_b32_e32 v109, 0xffff0000, v26
	v_pk_mul_f32 v[106:107], v[96:97], v[106:107] op_sel_hi:[0,1]
	v_pk_fma_f32 v[102:103], v[14:15], v[106:107], v[108:109]
	v_lshlrev_b32_e32 v106, 16, v35
	v_and_b32_e32 v107, 0xffff0000, v35
	v_lshlrev_b32_e32 v108, 16, v27
	v_and_b32_e32 v109, 0xffff0000, v27
	v_pk_mul_f32 v[106:107], v[96:97], v[106:107] op_sel_hi:[0,1]
	v_pk_fma_f32 v[104:105], v[16:17], v[106:107], v[108:109]
	global_store_dwordx4 v23, v[98:101], s[6:7]
	global_store_dwordx4 v23, v[102:105], s[6:7] offset:16
	v_lshlrev_b32_e32 v106, 16, v36
	v_and_b32_e32 v107, 0xffff0000, v36
	v_lshlrev_b32_e32 v108, 16, v28
	v_and_b32_e32 v109, 0xffff0000, v28
	v_pk_mul_f32 v[106:107], v[96:97], v[106:107] op_sel_hi:[0,1]
	v_pk_fma_f32 v[98:99], v[2:3], v[106:107], v[108:109]
	v_lshlrev_b32_e32 v106, 16, v37
	v_and_b32_e32 v107, 0xffff0000, v37
	v_lshlrev_b32_e32 v108, 16, v29
	v_and_b32_e32 v109, 0xffff0000, v29
	v_pk_mul_f32 v[106:107], v[96:97], v[106:107] op_sel_hi:[0,1]
	v_pk_fma_f32 v[100:101], v[4:5], v[106:107], v[108:109]
	v_lshlrev_b32_e32 v106, 16, v38
	v_and_b32_e32 v107, 0xffff0000, v38
	v_lshlrev_b32_e32 v108, 16, v30
	v_and_b32_e32 v109, 0xffff0000, v30
	v_pk_mul_f32 v[106:107], v[96:97], v[106:107] op_sel_hi:[0,1]
	v_pk_fma_f32 v[102:103], v[6:7], v[106:107], v[108:109]
	v_lshlrev_b32_e32 v106, 16, v39
	v_and_b32_e32 v107, 0xffff0000, v39
	v_lshlrev_b32_e32 v108, 16, v31
	v_and_b32_e32 v109, 0xffff0000, v31
	v_pk_mul_f32 v[106:107], v[96:97], v[106:107] op_sel_hi:[0,1]
	v_pk_fma_f32 v[104:105], v[8:9], v[106:107], v[108:109]
	global_store_dwordx4 v23, v[98:101], s[6:7] offset:2048
	global_store_dwordx4 v23, v[102:105], s[6:7] offset:2064
	v_add_u32_e32 v18, 0x400000, v18
	v_add_u32_e32 v20, 0x400000, v20
	v_add_u32_e32 v21, 0x2000, v21
	global_load_dwordx4 v[24:27], v18, s[4:5]
	global_load_dwordx4 v[32:35], v20, s[4:5]
	global_load_dwordx4 v[28:31], v18, s[4:5] offset:1024
	global_load_dwordx4 v[36:39], v20, s[4:5] offset:1024
	global_load_dword v40, v21, s[4:5]
	s_waitcnt vmcnt(27)
; __device__ __forceinline__ float bflo(unsigned w) { return __uint_as_float(w << 16); }
; __device__ __forceinline__ float bfhi(unsigned w) { return __uint_as_float(w & 0xffff0000u); }
; __device__ __forceinline__ void resid_rows(bf16_t* R, const bf16_t* Y, const float* ssqY, const float* g, float* rstd_out, float* outf, bool wf32, int row_lo, int row_hi, int yoff, int gw, int NGW, int lane) {
;     ...
;         for (int k = 0; k < RP; ++k) { const int row = row0 + k * NGW; const bool ok = row < row_hi; const int rw = ok ? row : row0;
;             ssv[k] = ssqY[rw];
; #pragma unroll
;             for (int j = 0; j < 2; ++j) { const int c = 8 * lane + 512 * j; rr[k][j] = *(const u32x4*)(R + (size_t)rw * DM + c); oo[k][j] = *(const u32x4*)(Y + (size_t)(rw - yoff) * DM + c); } }
; #pragma unroll
;         for (int k = 0; k < RP; ++k) { const int row = row0 + k * NGW; if (row < row_hi) {
;             const float rs = __builtin_amdgcn_rsqf(ssv[k] * (1.0f / DM) + RMS_EPS); float s = 0.f;
; #pragma unroll
;             for (int j = 0; j < 2; ++j) { const int c = 8 * lane + 512 * j; const u32x4 r = rr[k][j], o = oo[k][j]; const f32x4 ga = gv[j][0], gb = gv[j][1];
;                 f32x4 ya, yb; ya[0] = bflo(r.x) + bflo(o.x) * rs * ga[0]; ya[1] = bfhi(r.x) + bfhi(o.x) * rs * ga[1]; ya[2] = bflo(r.y) + bflo(o.y) * rs * ga[2]; ya[3] = bfhi(r.y) + bfhi(o.y) * rs * ga[3];
;                 yb[0] = bflo(r.z) + bflo(o.z) * rs * gb[0]; yb[1] = bfhi(r.z) + bfhi(o.z) * rs * gb[1]; yb[2] = bflo(r.w) + bflo(o.w) * rs * gb[2]; yb[3] = bfhi(r.w) + bfhi(o.w) * rs * gb[3];
;                 if (wf32) { *(f32x4*)(outf + (size_t)row * DM + c) = ya; *(f32x4*)(outf + (size_t)row * DM + c + 4) = yb; }
;                 s += (ya[0] * ya[0] + ya[1] * ya[1]) + (ya[2] * ya[2] + ya[3] * ya[3]) + (yb[0] * yb[0] + yb[1] * yb[1]) + (yb[2] * yb[2] + yb[3] * yb[3]);
;                 u32x4 w; w.x = pk2(ya[0], ya[1]); w.y = pk2(ya[2], ya[3]); w.z = pk2(yb[0], yb[1]); w.w = pk2(yb[2], yb[3]); *(u32x4*)(R + (size_t)row * DM + c) = w; }
	v_fmamk_f32 v96, v58, 0x3a800000, v244
	v_rsq_f32_e32 v96, v96
	v_add_u32_e32 v23, 0x800000, v23
	v_lshlrev_b32_e32 v106, 16, v50
	v_and_b32_e32 v107, 0xffff0000, v50
	v_lshlrev_b32_e32 v108, 16, v42
	v_and_b32_e32 v109, 0xffff0000, v42
	v_pk_mul_f32 v[106:107], v[96:97], v[106:107] op_sel_hi:[0,1]
	v_pk_fma_f32 v[98:99], v[10:11], v[106:107], v[108:109]
	v_lshlrev_b32_e32 v106, 16, v51
	v_and_b32_e32 v107, 0xffff0000, v51
	v_lshlrev_b32_e32 v108, 16, v43
	v_and_b32_e32 v109, 0xffff0000, v43
	v_pk_mul_f32 v[106:107], v[96:97], v[106:107] op_sel_hi:[0,1]
	v_pk_fma_f32 v[100:101], v[12:13], v[106:107], v[108:109]
	v_lshlrev_b32_e32 v106, 16, v52
	v_and_b32_e32 v107, 0xffff0000, v52
	v_lshlrev_b32_e32 v108, 16, v44
	v_and_b32_e32 v109, 0xffff0000, v44
	v_pk_mul_f32 v[106:107], v[96:97], v[106:107] op_sel_hi:[0,1]
	v_pk_fma_f32 v[102:103], v[14:15], v[106:107], v[108:109]
	v_lshlrev_b32_e32 v106, 16, v53
	v_and_b32_e32 v107, 0xffff0000, v53
	v_lshlrev_b32_e32 v108, 16, v45
	v_and_b32_e32 v109, 0xffff0000, v45
	v_pk_mul_f32 v[106:107], v[96:97], v[106:107] op_sel_hi:[0,1]
	v_pk_fma_f32 v[104:105], v[16:17], v[106:107], v[108:109]
	global_store_dwordx4 v23, v[98:101], s[6:7]
	global_store_dwordx4 v23, v[102:105], s[6:7] offset:16
	v_lshlrev_b32_e32 v106, 16, v54
	v_and_b32_e32 v107, 0xffff0000, v54
	v_lshlrev_b32_e32 v108, 16, v46
	v_and_b32_e32 v109, 0xffff0000, v46
	v_pk_mul_f32 v[106:107], v[96:97], v[106:107] op_sel_hi:[0,1]
	v_pk_fma_f32 v[98:99], v[2:3], v[106:107], v[108:109]
	v_lshlrev_b32_e32 v106, 16, v55
	v_and_b32_e32 v107, 0xffff0000, v55
	v_lshlrev_b32_e32 v108, 16, v47
	v_and_b32_e32 v109, 0xffff0000, v47
	v_pk_mul_f32 v[106:107], v[96:97], v[106:107] op_sel_hi:[0,1]
	v_pk_fma_f32 v[100:101], v[4:5], v[106:107], v[108:109]
	v_lshlrev_b32_e32 v106, 16, v56
	v_and_b32_e32 v107, 0xffff0000, v56
	v_lshlrev_b32_e32 v108, 16, v48
	v_and_b32_e32 v109, 0xffff0000, v48
	v_pk_mul_f32 v[106:107], v[96:97], v[106:107] op_sel_hi:[0,1]
	v_pk_fma_f32 v[102:103], v[6:7], v[106:107], v[108:109]
	v_lshlrev_b32_e32 v106, 16, v57
	v_and_b32_e32 v107, 0xffff0000, v57
	v_lshlrev_b32_e32 v108, 16, v49
	v_and_b32_e32 v109, 0xffff0000, v49
	v_pk_mul_f32 v[106:107], v[96:97], v[106:107] op_sel_hi:[0,1]
	v_pk_fma_f32 v[104:105], v[8:9], v[106:107], v[108:109]
	global_store_dwordx4 v23, v[98:101], s[6:7] offset:2048
	global_store_dwordx4 v23, v[102:105], s[6:7] offset:2064
	v_add_u32_e32 v18, 0x400000, v18
	v_add_u32_e32 v20, 0x400000, v20
	v_add_u32_e32 v21, 0x2000, v21
	global_load_dwordx4 v[42:45], v18, s[4:5]
	global_load_dwordx4 v[50:53], v20, s[4:5]
	global_load_dwordx4 v[46:49], v18, s[4:5] offset:1024
	global_load_dwordx4 v[54:57], v20, s[4:5] offset:1024
	global_load_dword v58, v21, s[4:5]
	s_waitcnt vmcnt(27)
	v_fmamk_f32 v96, v76, 0x3a800000, v244
	v_rsq_f32_e32 v96, v96
	v_add_u32_e32 v23, 0x800000, v23
	v_lshlrev_b32_e32 v106, 16, v68
	v_and_b32_e32 v107, 0xffff0000, v68
	v_lshlrev_b32_e32 v108, 16, v60
	v_and_b32_e32 v109, 0xffff0000, v60
	v_pk_mul_f32 v[106:107], v[96:97], v[106:107] op_sel_hi:[0,1]
	v_pk_fma_f32 v[98:99], v[10:11], v[106:107], v[108:109]
	v_lshlrev_b32_e32 v106, 16, v69
	v_and_b32_e32 v107, 0xffff0000, v69
	v_lshlrev_b32_e32 v108, 16, v61
	v_and_b32_e32 v109, 0xffff0000, v61
	v_pk_mul_f32 v[106:107], v[96:97], v[106:107] op_sel_hi:[0,1]
	v_pk_fma_f32 v[100:101], v[12:13], v[106:107], v[108:109]
	v_lshlrev_b32_e32 v106, 16, v70
	v_and_b32_e32 v107, 0xffff0000, v70
	v_lshlrev_b32_e32 v108, 16, v62
	v_and_b32_e32 v109, 0xffff0000, v62
	v_pk_mul_f32 v[106:107], v[96:97], v[106:107] op_sel_hi:[0,1]
	v_pk_fma_f32 v[102:103], v[14:15], v[106:107], v[108:109]
	v_lshlrev_b32_e32 v106, 16, v71
	v_and_b32_e32 v107, 0xffff0000, v71
	v_lshlrev_b32_e32 v108, 16, v63
	v_and_b32_e32 v109, 0xffff0000, v63
	v_pk_mul_f32 v[106:107], v[96:97], v[106:107] op_sel_hi:[0,1]
	v_pk_fma_f32 v[104:105], v[16:17], v[106:107], v[108:109]
	global_store_dwordx4 v23, v[98:101], s[6:7]
	global_store_dwordx4 v23, v[102:105], s[6:7] offset:16
	v_lshlrev_b32_e32 v106, 16, v72
	v_and_b32_e32 v107, 0xffff0000, v72
	v_lshlrev_b32_e32 v108, 16, v64
	v_and_b32_e32 v109, 0xffff0000, v64
	v_pk_mul_f32 v[106:107], v[96:97], v[106:107] op_sel_hi:[0,1]
	v_pk_fma_f32 v[98:99], v[2:3], v[106:107], v[108:109]
	v_lshlrev_b32_e32 v106, 16, v73
	v_and_b32_e32 v107, 0xffff0000, v73
	v_lshlrev_b32_e32 v108, 16, v65
	v_and_b32_e32 v109, 0xffff0000, v65
	v_pk_mul_f32 v[106:107], v[96:97], v[106:107] op_sel_hi:[0,1]
	v_pk_fma_f32 v[100:101], v[4:5], v[106:107], v[108:109]
	v_lshlrev_b32_e32 v106, 16, v74
	v_and_b32_e32 v107, 0xffff0000, v74
	v_lshlrev_b32_e32 v108, 16, v66
	v_and_b32_e32 v109, 0xffff0000, v66
	v_pk_mul_f32 v[106:107], v[96:97], v[106:107] op_sel_hi:[0,1]
	v_pk_fma_f32 v[102:103], v[6:7], v[106:107], v[108:109]
	v_lshlrev_b32_e32 v106, 16, v75
	v_and_b32_e32 v107, 0xffff0000, v75
	v_lshlrev_b32_e32 v108, 16, v67
	v_and_b32_e32 v109, 0xffff0000, v67
	v_pk_mul_f32 v[106:107], v[96:97], v[106:107] op_sel_hi:[0,1]
	v_pk_fma_f32 v[104:105], v[8:9], v[106:107], v[108:109]
	global_store_dwordx4 v23, v[98:101], s[6:7] offset:2048
	global_store_dwordx4 v23, v[102:105], s[6:7] offset:2064
	v_add_u32_e32 v18, 0x400000, v18
	v_add_u32_e32 v20, 0x400000, v20
	v_add_u32_e32 v21, 0x2000, v21
	global_load_dwordx4 v[60:63], v18, s[4:5]
	global_load_dwordx4 v[68:71], v20, s[4:5]
	global_load_dwordx4 v[64:67], v18, s[4:5] offset:1024
	global_load_dwordx4 v[72:75], v20, s[4:5] offset:1024
	global_load_dword v76, v21, s[4:5]
	s_waitcnt vmcnt(27)
; __device__ __forceinline__ float bflo(unsigned w) { return __uint_as_float(w << 16); }
; __device__ __forceinline__ float bfhi(unsigned w) { return __uint_as_float(w & 0xffff0000u); }
; __device__ __forceinline__ void resid_rows(bf16_t* R, const bf16_t* Y, const float* ssqY, const float* g, float* rstd_out, float* outf, bool wf32, int row_lo, int row_hi, int yoff, int gw, int NGW, int lane) {
;     ...
;         for (int k = 0; k < RP; ++k) { const int row = row0 + k * NGW; const bool ok = row < row_hi; const int rw = ok ? row : row0;
;             ssv[k] = ssqY[rw];
; #pragma unroll
;             for (int j = 0; j < 2; ++j) { const int c = 8 * lane + 512 * j; rr[k][j] = *(const u32x4*)(R + (size_t)rw * DM + c); oo[k][j] = *(const u32x4*)(Y + (size_t)(rw - yoff) * DM + c); } }
; #pragma unroll
;         for (int k = 0; k < RP; ++k) { const int row = row0 + k * NGW; if (row < row_hi) {
;             const float rs = __builtin_amdgcn_rsqf(ssv[k] * (1.0f / DM) + RMS_EPS); float s = 0.f;
; #pragma unroll
;             for (int j = 0; j < 2; ++j) { const int c = 8 * lane + 512 * j; const u32x4 r = rr[k][j], o = oo[k][j]; const f32x4 ga = gv[j][0], gb = gv[j][1];
;                 f32x4 ya, yb; ya[0] = bflo(r.x) + bflo(o.x) * rs * ga[0]; ya[1] = bfhi(r.x) + bfhi(o.x) * rs * ga[1]; ya[2] = bflo(r.y) + bflo(o.y) * rs * ga[2]; ya[3] = bfhi(r.y) + bfhi(o.y) * rs * ga[3];
;                 yb[0] = bflo(r.z) + bflo(o.z) * rs * gb[0]; yb[1] = bfhi(r.z) + bfhi(o.z) * rs * gb[1]; yb[2] = bflo(r.w) + bflo(o.w) * rs * gb[2]; yb[3] = bfhi(r.w) + bfhi(o.w) * rs * gb[3];
;                 if (wf32) { *(f32x4*)(outf + (size_t)row * DM + c) = ya; *(f32x4*)(outf + (size_t)row * DM + c + 4) = yb; }
;                 s += (ya[0] * ya[0] + ya[1] * ya[1]) + (ya[2] * ya[2] + ya[3] * ya[3]) + (yb[0] * yb[0] + yb[1] * yb[1]) + (yb[2] * yb[2] + yb[3] * yb[3]);
;                 u32x4 w; w.x = pk2(ya[0], ya[1]); w.y = pk2(ya[2], ya[3]); w.z = pk2(yb[0], yb[1]); w.w = pk2(yb[2], yb[3]); *(u32x4*)(R + (size_t)row * DM + c) = w; }
	v_fmamk_f32 v96, v94, 0x3a800000, v244
	v_rsq_f32_e32 v96, v96
	v_add_u32_e32 v23, 0x800000, v23
	v_lshlrev_b32_e32 v106, 16, v86
	v_and_b32_e32 v107, 0xffff0000, v86
	v_lshlrev_b32_e32 v108, 16, v78
	v_and_b32_e32 v109, 0xffff0000, v78
	v_pk_mul_f32 v[106:107], v[96:97], v[106:107] op_sel_hi:[0,1]
	v_pk_fma_f32 v[98:99], v[10:11], v[106:107], v[108:109]
	v_lshlrev_b32_e32 v106, 16, v87
	v_and_b32_e32 v107, 0xffff0000, v87
	v_lshlrev_b32_e32 v108, 16, v79
	v_and_b32_e32 v109, 0xffff0000, v79
	v_pk_mul_f32 v[106:107], v[96:97], v[106:107] op_sel_hi:[0,1]
	v_pk_fma_f32 v[100:101], v[12:13], v[106:107], v[108:109]
	v_lshlrev_b32_e32 v106, 16, v88
	v_and_b32_e32 v107, 0xffff0000, v88
	v_lshlrev_b32_e32 v108, 16, v80
	v_and_b32_e32 v109, 0xffff0000, v80
	v_pk_mul_f32 v[106:107], v[96:97], v[106:107] op_sel_hi:[0,1]
	v_pk_fma_f32 v[102:103], v[14:15], v[106:107], v[108:109]
	v_lshlrev_b32_e32 v106, 16, v89
	v_and_b32_e32 v107, 0xffff0000, v89
	v_lshlrev_b32_e32 v108, 16, v81
	v_and_b32_e32 v109, 0xffff0000, v81
	v_pk_mul_f32 v[106:107], v[96:97], v[106:107] op_sel_hi:[0,1]
	v_pk_fma_f32 v[104:105], v[16:17], v[106:107], v[108:109]
	global_store_dwordx4 v23, v[98:101], s[6:7]
	global_store_dwordx4 v23, v[102:105], s[6:7] offset:16
	v_lshlrev_b32_e32 v106, 16, v90
	v_and_b32_e32 v107, 0xffff0000, v90
	v_lshlrev_b32_e32 v108, 16, v82
	v_and_b32_e32 v109, 0xffff0000, v82
	v_pk_mul_f32 v[106:107], v[96:97], v[106:107] op_sel_hi:[0,1]
	v_pk_fma_f32 v[98:99], v[2:3], v[106:107], v[108:109]
	v_lshlrev_b32_e32 v106, 16, v91
	v_and_b32_e32 v107, 0xffff0000, v91
	v_lshlrev_b32_e32 v108, 16, v83
	v_and_b32_e32 v109, 0xffff0000, v83
	v_pk_mul_f32 v[106:107], v[96:97], v[106:107] op_sel_hi:[0,1]
	v_pk_fma_f32 v[100:101], v[4:5], v[106:107], v[108:109]
	v_lshlrev_b32_e32 v106, 16, v92
	v_and_b32_e32 v107, 0xffff0000, v92
	v_lshlrev_b32_e32 v108, 16, v84
	v_and_b32_e32 v109, 0xffff0000, v84
	v_pk_mul_f32 v[106:107], v[96:97], v[106:107] op_sel_hi:[0,1]
	v_pk_fma_f32 v[102:103], v[6:7], v[106:107], v[108:109]
	v_lshlrev_b32_e32 v106, 16, v93
	v_and_b32_e32 v107, 0xffff0000, v93
	v_lshlrev_b32_e32 v108, 16, v85
	v_and_b32_e32 v109, 0xffff0000, v85
	v_pk_mul_f32 v[106:107], v[96:97], v[106:107] op_sel_hi:[0,1]
	v_pk_fma_f32 v[104:105], v[8:9], v[106:107], v[108:109]
	global_store_dwordx4 v23, v[98:101], s[6:7] offset:2048
	global_store_dwordx4 v23, v[102:105], s[6:7] offset:2064
	v_add_u32_e32 v18, 0x400000, v18
	v_add_u32_e32 v20, 0x400000, v20
	v_add_u32_e32 v21, 0x2000, v21
	global_load_dwordx4 v[78:81], v18, s[4:5]
	global_load_dwordx4 v[86:89], v20, s[4:5]
	global_load_dwordx4 v[82:85], v18, s[4:5] offset:1024
	global_load_dwordx4 v[90:93], v20, s[4:5] offset:1024
	global_load_dword v94, v21, s[4:5]
	s_waitcnt vmcnt(27)
	v_fmamk_f32 v96, v40, 0x3a800000, v244
	v_rsq_f32_e32 v96, v96
	v_add_u32_e32 v23, 0x800000, v23
	v_lshlrev_b32_e32 v106, 16, v32
	v_and_b32_e32 v107, 0xffff0000, v32
	v_lshlrev_b32_e32 v108, 16, v24
	v_and_b32_e32 v109, 0xffff0000, v24
	v_pk_mul_f32 v[106:107], v[96:97], v[106:107] op_sel_hi:[0,1]
	v_pk_fma_f32 v[98:99], v[10:11], v[106:107], v[108:109]
	v_lshlrev_b32_e32 v106, 16, v33
	v_and_b32_e32 v107, 0xffff0000, v33
	v_lshlrev_b32_e32 v108, 16, v25
	v_and_b32_e32 v109, 0xffff0000, v25
	v_pk_mul_f32 v[106:107], v[96:97], v[106:107] op_sel_hi:[0,1]
	v_pk_fma_f32 v[100:101], v[12:13], v[106:107], v[108:109]
	v_lshlrev_b32_e32 v106, 16, v34
	v_and_b32_e32 v107, 0xffff0000, v34
	v_lshlrev_b32_e32 v108, 16, v26
	v_and_b32_e32 v109, 0xffff0000, v26
	v_pk_mul_f32 v[106:107], v[96:97], v[106:107] op_sel_hi:[0,1]
	v_pk_fma_f32 v[102:103], v[14:15], v[106:107], v[108:109]
	v_lshlrev_b32_e32 v106, 16, v35
	v_and_b32_e32 v107, 0xffff0000, v35
	v_lshlrev_b32_e32 v108, 16, v27
	v_and_b32_e32 v109, 0xffff0000, v27
	v_pk_mul_f32 v[106:107], v[96:97], v[106:107] op_sel_hi:[0,1]
	v_pk_fma_f32 v[104:105], v[16:17], v[106:107], v[108:109]
	global_store_dwordx4 v23, v[98:101], s[6:7]
	global_store_dwordx4 v23, v[102:105], s[6:7] offset:16
	v_lshlrev_b32_e32 v106, 16, v36
	v_and_b32_e32 v107, 0xffff0000, v36
	v_lshlrev_b32_e32 v108, 16, v28
	v_and_b32_e32 v109, 0xffff0000, v28
	v_pk_mul_f32 v[106:107], v[96:97], v[106:107] op_sel_hi:[0,1]
	v_pk_fma_f32 v[98:99], v[2:3], v[106:107], v[108:109]
	v_lshlrev_b32_e32 v106, 16, v37
	v_and_b32_e32 v107, 0xffff0000, v37
	v_lshlrev_b32_e32 v108, 16, v29
	v_and_b32_e32 v109, 0xffff0000, v29
	v_pk_mul_f32 v[106:107], v[96:97], v[106:107] op_sel_hi:[0,1]
	v_pk_fma_f32 v[100:101], v[4:5], v[106:107], v[108:109]
	v_lshlrev_b32_e32 v106, 16, v38
	v_and_b32_e32 v107, 0xffff0000, v38
	v_lshlrev_b32_e32 v108, 16, v30
	v_and_b32_e32 v109, 0xffff0000, v30
	v_pk_mul_f32 v[106:107], v[96:97], v[106:107] op_sel_hi:[0,1]
	v_pk_fma_f32 v[102:103], v[6:7], v[106:107], v[108:109]
	v_lshlrev_b32_e32 v106, 16, v39
	v_and_b32_e32 v107, 0xffff0000, v39
	v_lshlrev_b32_e32 v108, 16, v31
	v_and_b32_e32 v109, 0xffff0000, v31
	v_pk_mul_f32 v[106:107], v[96:97], v[106:107] op_sel_hi:[0,1]
	v_pk_fma_f32 v[104:105], v[8:9], v[106:107], v[108:109]
	global_store_dwordx4 v23, v[98:101], s[6:7] offset:2048
	global_store_dwordx4 v23, v[102:105], s[6:7] offset:2064
	s_nop 1
	s_waitcnt vmcnt(22)
; __device__ __forceinline__ float bflo(unsigned w) { return __uint_as_float(w << 16); }
; __device__ __forceinline__ float bfhi(unsigned w) { return __uint_as_float(w & 0xffff0000u); }
; __device__ __forceinline__ void resid_rows(bf16_t* R, const bf16_t* Y, const float* ssqY, const float* g, float* rstd_out, float* outf, bool wf32, int row_lo, int row_hi, int yoff, int gw, int NGW, int lane) {
;     ...
;         for (int k = 0; k < RP; ++k) { const int row = row0 + k * NGW; const bool ok = row < row_hi; const int rw = ok ? row : row0;
;             ssv[k] = ssqY[rw];
; #pragma unroll
;             for (int j = 0; j < 2; ++j) { const int c = 8 * lane + 512 * j; rr[k][j] = *(const u32x4*)(R + (size_t)rw * DM + c); oo[k][j] = *(const u32x4*)(Y + (size_t)(rw - yoff) * DM + c); } }
; #pragma unroll
;         for (int k = 0; k < RP; ++k) { const int row = row0 + k * NGW; if (row < row_hi) {
;             const float rs = __builtin_amdgcn_rsqf(ssv[k] * (1.0f / DM) + RMS_EPS); float s = 0.f;
; #pragma unroll
;             for (int j = 0; j < 2; ++j) { const int c = 8 * lane + 512 * j; const u32x4 r = rr[k][j], o = oo[k][j]; const f32x4 ga = gv[j][0], gb = gv[j][1];
;                 f32x4 ya, yb; ya[0] = bflo(r.x) + bflo(o.x) * rs * ga[0]; ya[1] = bfhi(r.x) + bfhi(o.x) * rs * ga[1]; ya[2] = bflo(r.y) + bflo(o.y) * rs * ga[2]; ya[3] = bfhi(r.y) + bfhi(o.y) * rs * ga[3];
;                 yb[0] = bflo(r.z) + bflo(o.z) * rs * gb[0]; yb[1] = bfhi(r.z) + bfhi(o.z) * rs * gb[1]; yb[2] = bflo(r.w) + bflo(o.w) * rs * gb[2]; yb[3] = bfhi(r.w) + bfhi(o.w) * rs * gb[3];
;                 if (wf32) { *(f32x4*)(outf + (size_t)row * DM + c) = ya; *(f32x4*)(outf + (size_t)row * DM + c + 4) = yb; }
;                 s += (ya[0] * ya[0] + ya[1] * ya[1]) + (ya[2] * ya[2] + ya[3] * ya[3]) + (yb[0] * yb[0] + yb[1] * yb[1]) + (yb[2] * yb[2] + yb[3] * yb[3]);
;                 u32x4 w; w.x = pk2(ya[0], ya[1]); w.y = pk2(ya[2], ya[3]); w.z = pk2(yb[0], yb[1]); w.w = pk2(yb[2], yb[3]); *(u32x4*)(R + (size_t)row * DM + c) = w; }
	v_fmamk_f32 v96, v58, 0x3a800000, v244
	v_rsq_f32_e32 v96, v96
	v_add_u32_e32 v23, 0x800000, v23
	v_lshlrev_b32_e32 v106, 16, v50
	v_and_b32_e32 v107, 0xffff0000, v50
	v_lshlrev_b32_e32 v108, 16, v42
	v_and_b32_e32 v109, 0xffff0000, v42
	v_pk_mul_f32 v[106:107], v[96:97], v[106:107] op_sel_hi:[0,1]
	v_pk_fma_f32 v[98:99], v[10:11], v[106:107], v[108:109]
	v_lshlrev_b32_e32 v106, 16, v51
	v_and_b32_e32 v107, 0xffff0000, v51
	v_lshlrev_b32_e32 v108, 16, v43
	v_and_b32_e32 v109, 0xffff0000, v43
	v_pk_mul_f32 v[106:107], v[96:97], v[106:107] op_sel_hi:[0,1]
	v_pk_fma_f32 v[100:101], v[12:13], v[106:107], v[108:109]
	v_lshlrev_b32_e32 v106, 16, v52
	v_and_b32_e32 v107, 0xffff0000, v52
	v_lshlrev_b32_e32 v108, 16, v44
	v_and_b32_e32 v109, 0xffff0000, v44
	v_pk_mul_f32 v[106:107], v[96:97], v[106:107] op_sel_hi:[0,1]
	v_pk_fma_f32 v[102:103], v[14:15], v[106:107], v[108:109]
	v_lshlrev_b32_e32 v106, 16, v53
	v_and_b32_e32 v107, 0xffff0000, v53
	v_lshlrev_b32_e32 v108, 16, v45
	v_and_b32_e32 v109, 0xffff0000, v45
	v_pk_mul_f32 v[106:107], v[96:97], v[106:107] op_sel_hi:[0,1]
	v_pk_fma_f32 v[104:105], v[16:17], v[106:107], v[108:109]
	global_store_dwordx4 v23, v[98:101], s[6:7]
	global_store_dwordx4 v23, v[102:105], s[6:7] offset:16
	v_lshlrev_b32_e32 v106, 16, v54
	v_and_b32_e32 v107, 0xffff0000, v54
	v_lshlrev_b32_e32 v108, 16, v46
	v_and_b32_e32 v109, 0xffff0000, v46
	v_pk_mul_f32 v[106:107], v[96:97], v[106:107] op_sel_hi:[0,1]
	v_pk_fma_f32 v[98:99], v[2:3], v[106:107], v[108:109]
	v_lshlrev_b32_e32 v106, 16, v55
	v_and_b32_e32 v107, 0xffff0000, v55
	v_lshlrev_b32_e32 v108, 16, v47
	v_and_b32_e32 v109, 0xffff0000, v47
	v_pk_mul_f32 v[106:107], v[96:97], v[106:107] op_sel_hi:[0,1]
	v_pk_fma_f32 v[100:101], v[4:5], v[106:107], v[108:109]
	v_lshlrev_b32_e32 v106, 16, v56
	v_and_b32_e32 v107, 0xffff0000, v56
	v_lshlrev_b32_e32 v108, 16, v48
	v_and_b32_e32 v109, 0xffff0000, v48
	v_pk_mul_f32 v[106:107], v[96:97], v[106:107] op_sel_hi:[0,1]
	v_pk_fma_f32 v[102:103], v[6:7], v[106:107], v[108:109]
	v_lshlrev_b32_e32 v106, 16, v57
	v_and_b32_e32 v107, 0xffff0000, v57
	v_lshlrev_b32_e32 v108, 16, v49
	v_and_b32_e32 v109, 0xffff0000, v49
	v_pk_mul_f32 v[106:107], v[96:97], v[106:107] op_sel_hi:[0,1]
	v_pk_fma_f32 v[104:105], v[8:9], v[106:107], v[108:109]
	global_store_dwordx4 v23, v[98:101], s[6:7] offset:2048
	global_store_dwordx4 v23, v[102:105], s[6:7] offset:2064
	s_nop 1
	s_waitcnt vmcnt(17)
; __device__ __forceinline__ float bflo(unsigned w) { return __uint_as_float(w << 16); }
; __device__ __forceinline__ float bfhi(unsigned w) { return __uint_as_float(w & 0xffff0000u); }
; __device__ __forceinline__ void resid_rows(bf16_t* R, const bf16_t* Y, const float* ssqY, const float* g, float* rstd_out, float* outf, bool wf32, int row_lo, int row_hi, int yoff, int gw, int NGW, int lane) {
;     ...
;         for (int k = 0; k < RP; ++k) { const int row = row0 + k * NGW; const bool ok = row < row_hi; const int rw = ok ? row : row0;
;             ssv[k] = ssqY[rw];
; #pragma unroll
;             for (int j = 0; j < 2; ++j) { const int c = 8 * lane + 512 * j; rr[k][j] = *(const u32x4*)(R + (size_t)rw * DM + c); oo[k][j] = *(const u32x4*)(Y + (size_t)(rw - yoff) * DM + c); } }
; #pragma unroll
;         for (int k = 0; k < RP; ++k) { const int row = row0 + k * NGW; if (row < row_hi) {
;             const float rs = __builtin_amdgcn_rsqf(ssv[k] * (1.0f / DM) + RMS_EPS); float s = 0.f;
; #pragma unroll
;             for (int j = 0; j < 2; ++j) { const int c = 8 * lane + 512 * j; const u32x4 r = rr[k][j], o = oo[k][j]; const f32x4 ga = gv[j][0], gb = gv[j][1];
;                 f32x4 ya, yb; ya[0] = bflo(r.x) + bflo(o.x) * rs * ga[0]; ya[1] = bfhi(r.x) + bfhi(o.x) * rs * ga[1]; ya[2] = bflo(r.y) + bflo(o.y) * rs * ga[2]; ya[3] = bfhi(r.y) + bfhi(o.y) * rs * ga[3];
;                 yb[0] = bflo(r.z) + bflo(o.z) * rs * gb[0]; yb[1] = bfhi(r.z) + bfhi(o.z) * rs * gb[1]; yb[2] = bflo(r.w) + bflo(o.w) * rs * gb[2]; yb[3] = bfhi(r.w) + bfhi(o.w) * rs * gb[3];
;                 if (wf32) { *(f32x4*)(outf + (size_t)row * DM + c) = ya; *(f32x4*)(outf + (size_t)row * DM + c + 4) = yb; }
;                 s += (ya[0] * ya[0] + ya[1] * ya[1]) + (ya[2] * ya[2] + ya[3] * ya[3]) + (yb[0] * yb[0] + yb[1] * yb[1]) + (yb[2] * yb[2] + yb[3] * yb[3]);
;                 u32x4 w; w.x = pk2(ya[0], ya[1]); w.y = pk2(ya[2], ya[3]); w.z = pk2(yb[0], yb[1]); w.w = pk2(yb[2], yb[3]); *(u32x4*)(R + (size_t)row * DM + c) = w; }
	v_fmamk_f32 v96, v76, 0x3a800000, v244
	v_rsq_f32_e32 v96, v96
	v_add_u32_e32 v23, 0x800000, v23
	v_lshlrev_b32_e32 v106, 16, v68
	v_and_b32_e32 v107, 0xffff0000, v68
	v_lshlrev_b32_e32 v108, 16, v60
	v_and_b32_e32 v109, 0xffff0000, v60
	v_pk_mul_f32 v[106:107], v[96:97], v[106:107] op_sel_hi:[0,1]
	v_pk_fma_f32 v[98:99], v[10:11], v[106:107], v[108:109]
	v_lshlrev_b32_e32 v106, 16, v69
	v_and_b32_e32 v107, 0xffff0000, v69
	v_lshlrev_b32_e32 v108, 16, v61
	v_and_b32_e32 v109, 0xffff0000, v61
	v_pk_mul_f32 v[106:107], v[96:97], v[106:107] op_sel_hi:[0,1]
	v_pk_fma_f32 v[100:101], v[12:13], v[106:107], v[108:109]
	v_lshlrev_b32_e32 v106, 16, v70
	v_and_b32_e32 v107, 0xffff0000, v70
	v_lshlrev_b32_e32 v108, 16, v62
	v_and_b32_e32 v109, 0xffff0000, v62
	v_pk_mul_f32 v[106:107], v[96:97], v[106:107] op_sel_hi:[0,1]
	v_pk_fma_f32 v[102:103], v[14:15], v[106:107], v[108:109]
	v_lshlrev_b32_e32 v106, 16, v71
	v_and_b32_e32 v107, 0xffff0000, v71
	v_lshlrev_b32_e32 v108, 16, v63
	v_and_b32_e32 v109, 0xffff0000, v63
	v_pk_mul_f32 v[106:107], v[96:97], v[106:107] op_sel_hi:[0,1]
	v_pk_fma_f32 v[104:105], v[16:17], v[106:107], v[108:109]
	global_store_dwordx4 v23, v[98:101], s[6:7]
	global_store_dwordx4 v23, v[102:105], s[6:7] offset:16
	v_lshlrev_b32_e32 v106, 16, v72
	v_and_b32_e32 v107, 0xffff0000, v72
	v_lshlrev_b32_e32 v108, 16, v64
	v_and_b32_e32 v109, 0xffff0000, v64
	v_pk_mul_f32 v[106:107], v[96:97], v[106:107] op_sel_hi:[0,1]
	v_pk_fma_f32 v[98:99], v[2:3], v[106:107], v[108:109]
	v_lshlrev_b32_e32 v106, 16, v73
	v_and_b32_e32 v107, 0xffff0000, v73
	v_lshlrev_b32_e32 v108, 16, v65
	v_and_b32_e32 v109, 0xffff0000, v65
	v_pk_mul_f32 v[106:107], v[96:97], v[106:107] op_sel_hi:[0,1]
	v_pk_fma_f32 v[100:101], v[4:5], v[106:107], v[108:109]
	v_lshlrev_b32_e32 v106, 16, v74
	v_and_b32_e32 v107, 0xffff0000, v74
	v_lshlrev_b32_e32 v108, 16, v66
	v_and_b32_e32 v109, 0xffff0000, v66
	v_pk_mul_f32 v[106:107], v[96:97], v[106:107] op_sel_hi:[0,1]
	v_pk_fma_f32 v[102:103], v[6:7], v[106:107], v[108:109]
	v_lshlrev_b32_e32 v106, 16, v75
	v_and_b32_e32 v107, 0xffff0000, v75
	v_lshlrev_b32_e32 v108, 16, v67
	v_and_b32_e32 v109, 0xffff0000, v67
	v_pk_mul_f32 v[106:107], v[96:97], v[106:107] op_sel_hi:[0,1]
	v_pk_fma_f32 v[104:105], v[8:9], v[106:107], v[108:109]
	global_store_dwordx4 v23, v[98:101], s[6:7] offset:2048
	global_store_dwordx4 v23, v[102:105], s[6:7] offset:2064
	s_nop 1
	s_waitcnt vmcnt(12)
	v_fmamk_f32 v96, v94, 0x3a800000, v244
	v_rsq_f32_e32 v96, v96
	v_add_u32_e32 v23, 0x800000, v23
	v_lshlrev_b32_e32 v106, 16, v86
	v_and_b32_e32 v107, 0xffff0000, v86
	v_lshlrev_b32_e32 v108, 16, v78
	v_and_b32_e32 v109, 0xffff0000, v78
	v_pk_mul_f32 v[106:107], v[96:97], v[106:107] op_sel_hi:[0,1]
	v_pk_fma_f32 v[98:99], v[10:11], v[106:107], v[108:109]
	v_lshlrev_b32_e32 v106, 16, v87
	v_and_b32_e32 v107, 0xffff0000, v87
	v_lshlrev_b32_e32 v108, 16, v79
	v_and_b32_e32 v109, 0xffff0000, v79
	v_pk_mul_f32 v[106:107], v[96:97], v[106:107] op_sel_hi:[0,1]
	v_pk_fma_f32 v[100:101], v[12:13], v[106:107], v[108:109]
	v_lshlrev_b32_e32 v106, 16, v88
	v_and_b32_e32 v107, 0xffff0000, v88
	v_lshlrev_b32_e32 v108, 16, v80
	v_and_b32_e32 v109, 0xffff0000, v80
	v_pk_mul_f32 v[106:107], v[96:97], v[106:107] op_sel_hi:[0,1]
	v_pk_fma_f32 v[102:103], v[14:15], v[106:107], v[108:109]
	v_lshlrev_b32_e32 v106, 16, v89
	v_and_b32_e32 v107, 0xffff0000, v89
	v_lshlrev_b32_e32 v108, 16, v81
	v_and_b32_e32 v109, 0xffff0000, v81
	v_pk_mul_f32 v[106:107], v[96:97], v[106:107] op_sel_hi:[0,1]
	v_pk_fma_f32 v[104:105], v[16:17], v[106:107], v[108:109]
	global_store_dwordx4 v23, v[98:101], s[6:7]
	global_store_dwordx4 v23, v[102:105], s[6:7] offset:16
	v_lshlrev_b32_e32 v106, 16, v90
	v_and_b32_e32 v107, 0xffff0000, v90
	v_lshlrev_b32_e32 v108, 16, v82
	v_and_b32_e32 v109, 0xffff0000, v82
	v_pk_mul_f32 v[106:107], v[96:97], v[106:107] op_sel_hi:[0,1]
	v_pk_fma_f32 v[98:99], v[2:3], v[106:107], v[108:109]
	v_lshlrev_b32_e32 v106, 16, v91
	v_and_b32_e32 v107, 0xffff0000, v91
	v_lshlrev_b32_e32 v108, 16, v83
	v_and_b32_e32 v109, 0xffff0000, v83
	v_pk_mul_f32 v[106:107], v[96:97], v[106:107] op_sel_hi:[0,1]
	v_pk_fma_f32 v[100:101], v[4:5], v[106:107], v[108:109]
	v_lshlrev_b32_e32 v106, 16, v92
	v_and_b32_e32 v107, 0xffff0000, v92
	v_lshlrev_b32_e32 v108, 16, v84
	v_and_b32_e32 v109, 0xffff0000, v84
	v_pk_mul_f32 v[106:107], v[96:97], v[106:107] op_sel_hi:[0,1]
	v_pk_fma_f32 v[102:103], v[6:7], v[106:107], v[108:109]
	v_lshlrev_b32_e32 v106, 16, v93
	v_and_b32_e32 v107, 0xffff0000, v93
	v_lshlrev_b32_e32 v108, 16, v85
	v_and_b32_e32 v109, 0xffff0000, v85
	v_pk_mul_f32 v[106:107], v[96:97], v[106:107] op_sel_hi:[0,1]
	v_pk_fma_f32 v[104:105], v[8:9], v[106:107], v[108:109]
	global_store_dwordx4 v23, v[98:101], s[6:7] offset:2048
	global_store_dwordx4 v23, v[102:105], s[6:7] offset:2064
	s_branch .LBB0_907
